# sgemm_sample: K-batch order rotated per workgroup so concurrent waves read different 512-byte column windows (L2 channel spread); sum order only
# baseline (speedup 1.0000x reference)
; #define LAS __attribute__((address_space(3)))
; __device__ __forceinline__ unsigned cvt_pk_bf16(float lo, float hi) { f32x2 f = {lo, hi}; bf16x2_t v = __builtin_convertvector(f, bf16x2_t); return __builtin_bit_cast(unsigned, v); }
; template <int MODE>
; __device__ __forceinline__ void sgemm_sample(LAS unsigned char* lds, const bf16_t* A, const bf16_t* Bt, int K, const float* resid, float* out, bf16_t* xb, float* ssq_out, const float* ssq_in) {
;     ...
;     for (int uu = u; uu < 2048; uu += gridDim.x * 8) {
;         const int rt = uu >> 6, ct = uu & 63; const int row = NTOKP + rt * 16 + fr, col0 = ct * 16 + fq * 4;
;         const bf16_t* ap = A + (size_t)row * K + fq * 8; const bf16_t* bp = Bt + (size_t)(ct * 16 + fr) * K + fq * 8;
;         f32x4 acc = {0.f, 0.f, 0.f, 0.f};
; #pragma unroll 8
;         for (int ks = 0; ks < K / 32; ++ks) {
;             const bf16x8 a = *(const bf16x8*)(ap + ks * 32); const bf16x8 b = *(const bf16x8*)(bp + ks * 32);
;             acc = __builtin_amdgcn_mfma_f32_16x16x32_bf16(b, a, acc, 0, 0, 0);
;         }
;         if (MODE == 0) {
;             const f32x4 x = *(const f32x4*)(resid + (size_t)(row - NTOKP) * D + col0) + acc;
;             *(f32x4*)(out + (size_t)row * D + col0) = x;
;             if (xb) { u32x2 wv; wv.x = cvt_pk_bf16(x[0], x[1]); wv.y = cvt_pk_bf16(x[2], x[3]); *(u32x2*)(xb + (size_t)row * D + col0) = wv; }
;             if (ssq_out) {
;                 float ss = (x[0] * x[0] + x[1] * x[1]) + (x[2] * x[2] + x[3] * x[3]); ss += __shfl_xor(ss, 16); ss += __shfl_xor(ss, 32);
;                 if (fq == 0) *(LAS float*)(lds + (w * 16 + fr) * 4) = ss;
;                 __syncthreads();
;                 if (tid < 16) { float t = 0.f;
; #pragma unroll
;                     for (int i = 0; i < 8; ++i) t += *(const LAS float*)(lds + (i * 16 + tid) * 4);
;                     const int g = (uu & 63) >> 3; float* sp = ssq_out + (size_t)(NTOKP + rt * 16 + tid) * 16; sp[g] = t; sp[8 + g] = 0.f; }
;                 __syncthreads();
;             }
.LBB0_894:
	s_and_b32 s6, s15, 63
	v_lshl_or_b32 v4, s6, 15, v21
	s_ashr_i32 s6, s3, 2
	s_and_b32 s6, s6, -16
	s_add_i32 s6, s6, 0x8000
	v_or_b32_e32 v12, s6, v17
	v_ashrrev_i32_e32 v13, 31, v12
	v_lshlrev_b64 v[8:9], 11, v[12:13]
	v_lshl_add_u64 v[10:11], v[6:7], 0, v[4:5]
	v_lshl_add_u64 v[14:15], v[6:7], 0, v[8:9]
	s_mov_b64 s[16:17], 0
	v_mov_b32_e32 v0, 0
	v_mov_b32_e32 v1, v5
	v_mov_b32_e32 v2, v5
	v_mov_b32_e32 v3, v5
	s_bfe_u32 s96, s2, 0x20003
	s_lshl_b32 s96, s96, 9
	s_mov_b32 s97, 0
.LBB0_895:
	v_lshl_add_u64 v[24:25], v[14:15], 0, s[96:97]
	v_add_co_u32_e32 v60, vcc, 0x15780000, v24
	v_lshl_add_u64 v[26:27], v[10:11], 0, s[96:97]
	s_add_i32 s96, s96, 0x200
	s_cmpk_eq_i32 s96, 0x800
	s_cselect_b32 s96, 0, s96
	s_nop 0
	v_addc_co_u32_e32 v61, vcc, 0, v25, vcc
	v_add_co_u32_e32 v62, vcc, 0x840000, v26
	s_add_u32 s16, s16, 0x200
	s_nop 0
	v_addc_co_u32_e32 v63, vcc, 0, v27, vcc
	global_load_dwordx4 v[24:27], v[60:61], off
	global_load_dwordx4 v[28:31], v[60:61], off offset:64
	global_load_dwordx4 v[32:35], v[60:61], off offset:128
	global_load_dwordx4 v[36:39], v[60:61], off offset:192
	global_load_dwordx4 v[40:43], v[60:61], off offset:256
	global_load_dwordx4 v[44:47], v[62:63], off
	global_load_dwordx4 v[48:51], v[62:63], off offset:64
	global_load_dwordx4 v[52:55], v[62:63], off offset:128
	global_load_dwordx4 v[56:59], v[62:63], off offset:192
	s_addc_u32 s17, s17, 0
	s_cmpk_eq_i32 s16, 0x800
	s_waitcnt vmcnt(3)
	v_mfma_f32_16x16x32_bf16 v[0:3], v[44:47], v[24:27], v[0:3]
	global_load_dwordx4 v[24:27], v[62:63], off offset:256
	s_waitcnt vmcnt(3)
	v_mfma_f32_16x16x32_bf16 v[0:3], v[48:51], v[28:31], v[0:3]
	global_load_dwordx4 v[28:31], v[62:63], off offset:320
	s_waitcnt vmcnt(3)
	v_mfma_f32_16x16x32_bf16 v[0:3], v[52:55], v[32:35], v[0:3]
	global_load_dwordx4 v[32:35], v[60:61], off offset:320
	s_waitcnt vmcnt(3)
	v_mfma_f32_16x16x32_bf16 v[0:3], v[56:59], v[36:39], v[0:3]
	global_load_dwordx4 v[36:39], v[62:63], off offset:384
	global_load_dwordx4 v[44:47], v[60:61], off offset:384
	s_waitcnt vmcnt(4)
	v_mfma_f32_16x16x32_bf16 v[0:3], v[24:27], v[40:43], v[0:3]
	global_load_dwordx4 v[24:27], v[62:63], off offset:448
	s_waitcnt vmcnt(3)
	v_mfma_f32_16x16x32_bf16 v[0:3], v[28:31], v[32:35], v[0:3]
	global_load_dwordx4 v[28:31], v[60:61], off offset:448
	s_waitcnt vmcnt(2)
	v_mfma_f32_16x16x32_bf16 v[0:3], v[36:39], v[44:47], v[0:3]
	s_waitcnt vmcnt(0)
	v_mfma_f32_16x16x32_bf16 v[0:3], v[24:27], v[28:31], v[0:3]
	s_cbranch_scc0 .LBB0_895
	s_and_b32 s18, s3, 63
	v_lshl_or_b32 v24, s18, 4, v18
	v_lshlrev_b64 v[14:15], 12, v[12:13]
	v_lshl_add_u64 v[10:11], s[40:41], 0, v[14:15]
	v_lshlrev_b32_e32 v4, 2, v24
	v_lshl_add_u64 v[10:11], v[10:11], 0, v[4:5]
	v_add_co_u32_e32 v10, vcc, 0xf8000000, v10
	v_lshl_add_u64 v[14:15], s[90:91], 0, v[14:15]
	s_nop 0
	v_addc_co_u32_e32 v11, vcc, -1, v11, vcc
	global_load_dwordx4 v[10:13], v[10:11], off
	s_waitcnt vmcnt(0)
	v_pk_add_f32 v[2:3], v[2:3], v[12:13]
	v_pk_add_f32 v[0:1], v[0:1], v[10:11]
	v_mul_f32_e32 v11, v3, v3
	v_mul_f32_e32 v10, v1, v1
	v_fmac_f32_e32 v10, v0, v0
	v_fmac_f32_e32 v11, v2, v2
	v_add_f32_e32 v12, v10, v11
	ds_bpermute_b32 v13, v19, v12
	v_lshl_add_u64 v[10:11], v[14:15], 0, v[4:5]
	global_store_dwordx4 v[10:11], v[0:3], off
	v_cvt_pk_bf16_f32 v10, v0, v1
	v_cvt_pk_bf16_f32 v11, v2, v3
	s_waitcnt lgkmcnt(0)
	v_add_f32_e32 v0, v12, v13
	ds_bpermute_b32 v1, v20, v0
	v_lshl_add_u64 v[2:3], s[10:11], 0, v[8:9]
	v_lshlrev_b32_e32 v4, 1, v24
	v_lshl_add_u64 v[2:3], v[2:3], 0, v[4:5]
	global_store_dwordx2 v[2:3], v[10:11], off
	s_and_saveexec_b64 s[16:17], s[0:1]
	s_cbranch_execz .LBB0_898
	s_waitcnt lgkmcnt(0)
	v_add_f32_e32 v0, v0, v1
	ds_write_b32 v22, v0

; #define LAS __attribute__((address_space(3)))
; __device__ __forceinline__ unsigned cvt_pk_bf16(float lo, float hi) { f32x2 f = {lo, hi}; bf16x2_t v = __builtin_convertvector(f, bf16x2_t); return __builtin_bit_cast(unsigned, v); }
; template <int MODE>
; __device__ __forceinline__ void sgemm_sample(LAS unsigned char* lds, const bf16_t* A, const bf16_t* Bt, int K, const float* resid, float* out, bf16_t* xb, float* ssq_out, const float* ssq_in) {
;     ...
;     for (int uu = u; uu < 2048; uu += gridDim.x * 8) {
;         const int rt = uu >> 6, ct = uu & 63; const int row = NTOKP + rt * 16 + fr, col0 = ct * 16 + fq * 4;
;         const bf16_t* ap = A + (size_t)row * K + fq * 8; const bf16_t* bp = Bt + (size_t)(ct * 16 + fr) * K + fq * 8;
;         f32x4 acc = {0.f, 0.f, 0.f, 0.f};
; #pragma unroll 8
;         for (int ks = 0; ks < K / 32; ++ks) {
;             const bf16x8 a = *(const bf16x8*)(ap + ks * 32); const bf16x8 b = *(const bf16x8*)(bp + ks * 32);
;             acc = __builtin_amdgcn_mfma_f32_16x16x32_bf16(b, a, acc, 0, 0, 0);
;         }
;         if (MODE == 0) {
;             const f32x4 x = *(const f32x4*)(resid + (size_t)(row - NTOKP) * D + col0) + acc;
;             *(f32x4*)(out + (size_t)row * D + col0) = x;
;             if (xb) { u32x2 wv; wv.x = cvt_pk_bf16(x[0], x[1]); wv.y = cvt_pk_bf16(x[2], x[3]); *(u32x2*)(xb + (size_t)row * D + col0) = wv; }
;             if (ssq_out) {
;                 float ss = (x[0] * x[0] + x[1] * x[1]) + (x[2] * x[2] + x[3] * x[3]); ss += __shfl_xor(ss, 16); ss += __shfl_xor(ss, 32);
;                 if (fq == 0) *(LAS float*)(lds + (w * 16 + fr) * 4) = ss;
;                 __syncthreads();
;                 if (tid < 16) { float t = 0.f;
; #pragma unroll
;                     for (int i = 0; i < 8; ++i) t += *(const LAS float*)(lds + (i * 16 + tid) * 4);
;                     const int g = (uu & 63) >> 3; float* sp = ssq_out + (size_t)(NTOKP + rt * 16 + tid) * 16; sp[g] = t; sp[8 + g] = 0.f; }
;                 __syncthreads();
;             }
;         } else {
;             const float sc = rs_from_parts(ssq_in + (size_t)row * 16) * 0.0625f;
;             u32x2 wv; wv.x = cvt_pk_bf16(acc[0] * sc, acc[1] * sc); wv.y = cvt_pk_bf16(acc[2] * sc, acc[3] * sc); *(u32x2*)(xb + (size_t)row * D + col0) = wv;
;         }
.LBB0_999:
	s_lshl_b32 s0, s7, 11
	s_and_b32 s0, s0, 0x1f8000
	v_lshl_or_b32 v4, v18, 1, s0
	s_ashr_i32 s0, s3, 2
	s_and_b32 s0, s0, -16
	v_add_u32_e32 v10, s0, v16
	v_ashrrev_i32_e32 v11, 31, v10
	v_lshlrev_b64 v[8:9], 11, v[10:11]
	v_lshl_add_u64 v[12:13], v[6:7], 0, v[4:5]
	v_lshl_add_u64 v[14:15], v[6:7], 0, v[8:9]
	s_mov_b64 s[0:1], 0
	v_mov_b32_e32 v0, 0
	v_mov_b32_e32 v1, v5
	v_mov_b32_e32 v2, v5
	v_mov_b32_e32 v3, v5
	s_bfe_u32 s96, s2, 0x20003
	s_lshl_b32 s96, s96, 9
	s_mov_b32 s97, 0
.LBB0_1000:
	v_lshl_add_u64 v[20:21], v[14:15], 0, s[96:97]
	v_add_co_u32_e32 v56, vcc, 0xa4c0000, v20
	v_lshl_add_u64 v[22:23], v[12:13], 0, s[96:97]
	s_add_i32 s96, s96, 0x200
	s_cmpk_eq_i32 s96, 0x800
	s_cselect_b32 s96, 0, s96
	s_nop 0
	v_addc_co_u32_e32 v57, vcc, 0, v21, vcc
	v_add_co_u32_e32 v58, vcc, 0xa40000, v22
	s_add_u32 s0, s0, 0x200
	s_nop 0
	v_addc_co_u32_e32 v59, vcc, 0, v23, vcc
	global_load_dwordx4 v[20:23], v[56:57], off
	global_load_dwordx4 v[24:27], v[56:57], off offset:64
	global_load_dwordx4 v[28:31], v[56:57], off offset:128
	global_load_dwordx4 v[32:35], v[56:57], off offset:192
	global_load_dwordx4 v[36:39], v[56:57], off offset:256
	global_load_dwordx4 v[40:43], v[58:59], off
	global_load_dwordx4 v[44:47], v[58:59], off offset:64
	global_load_dwordx4 v[48:51], v[58:59], off offset:128
	global_load_dwordx4 v[52:55], v[58:59], off offset:192
	s_addc_u32 s1, s1, 0
	s_cmpk_eq_i32 s0, 0x800
	s_waitcnt vmcnt(3)
	v_mfma_f32_16x16x32_bf16 v[0:3], v[40:43], v[20:23], v[0:3]
	global_load_dwordx4 v[20:23], v[58:59], off offset:256
	s_waitcnt vmcnt(3)
	v_mfma_f32_16x16x32_bf16 v[0:3], v[44:47], v[24:27], v[0:3]
	global_load_dwordx4 v[24:27], v[58:59], off offset:320
	s_waitcnt vmcnt(3)
	v_mfma_f32_16x16x32_bf16 v[0:3], v[48:51], v[28:31], v[0:3]
	global_load_dwordx4 v[28:31], v[56:57], off offset:320
	s_waitcnt vmcnt(3)
	v_mfma_f32_16x16x32_bf16 v[0:3], v[52:55], v[32:35], v[0:3]
	global_load_dwordx4 v[32:35], v[58:59], off offset:384
	global_load_dwordx4 v[40:43], v[56:57], off offset:384
	s_waitcnt vmcnt(4)
	v_mfma_f32_16x16x32_bf16 v[0:3], v[20:23], v[36:39], v[0:3]
	global_load_dwordx4 v[20:23], v[58:59], off offset:448
	s_waitcnt vmcnt(3)
	v_mfma_f32_16x16x32_bf16 v[0:3], v[24:27], v[28:31], v[0:3]
	global_load_dwordx4 v[24:27], v[56:57], off offset:448
	s_waitcnt vmcnt(2)
	v_mfma_f32_16x16x32_bf16 v[0:3], v[32:35], v[40:43], v[0:3]
	s_waitcnt vmcnt(0)
	v_mfma_f32_16x16x32_bf16 v[0:3], v[20:23], v[24:27], v[0:3]
	s_cbranch_scc0 .LBB0_1000
	v_lshlrev_b64 v[10:11], 6, v[10:11]
	v_lshl_add_u64 v[14:15], s[4:5], 0, v[10:11]
	global_load_dwordx4 v[10:13], v[14:15], off
	global_load_dwordx4 v[20:23], v[14:15], off offset:16
	global_load_dwordx4 v[24:27], v[14:15], off offset:32
	global_load_dwordx4 v[28:31], v[14:15], off offset:48
	s_lshl_b32 s0, s3, 4
	s_and_b32 s0, s0, 0x3f0
	v_lshl_add_u64 v[8:9], s[10:11], 0, v[8:9]
	s_add_i32 s3, s3, s6
	s_add_i32 s7, s7, s12
	s_cmpk_gt_i32 s3, 0x7ff
	s_waitcnt vmcnt(3)
	v_mov_b32_e32 v14, v11
	v_mov_b32_e32 v15, v12
	v_mov_b32_e32 v11, v13
	s_waitcnt vmcnt(2)
	v_mov_b32_e32 v12, v21
	v_mov_b32_e32 v13, v22
	v_mov_b32_e32 v21, v23
	v_pk_add_f32 v[10:11], v[14:15], v[10:11]
	v_pk_add_f32 v[12:13], v[12:13], v[20:21]
	v_pk_add_f32 v[10:11], v[10:11], v[10:11] op_sel:[0,1] op_sel_hi:[1,0]
	v_pk_add_f32 v[12:13], v[12:13], v[12:13] op_sel:[0,1] op_sel_hi:[1,0]
	s_waitcnt vmcnt(1)
	v_add_f32_e32 v22, v24, v25
	v_add_f32_e32 v24, v26, v27
	s_waitcnt vmcnt(0)
	v_mov_b32_e32 v23, v30
	v_mov_b32_e32 v25, v31
	v_mov_b32_e32 v11, v28
	v_mov_b32_e32 v13, v29
	v_pk_add_f32 v[14:15], v[22:23], v[24:25]
	v_pk_add_f32 v[10:11], v[10:11], v[12:13]
	s_nop 0
	v_pk_add_f32 v[10:11], v[10:11], v[14:15]
	s_nop 0
	v_add_f32_e32 v4, v10, v11
	v_fmamk_f32 v4, v4, 0x3a800000, v19
	v_mul_f32_e32 v10, 0x4b800000, v4
	v_cmp_gt_f32_e32 vcc, s13, v4
	s_nop 1
	v_cndmask_b32_e32 v4, v4, v10, vcc
	v_rsq_f32_e32 v10, v4
	v_or_b32_e32 v4, s0, v17
	v_lshlrev_b32_e32 v4, 1, v4
	v_lshl_add_u64 v[8:9], v[8:9], 0, v[4:5]
	v_mul_f32_e32 v4, 0x45800000, v10
	v_cndmask_b32_e32 v4, v10, v4, vcc
	v_mul_f32_e32 v4, 0x3d800000, v4
	v_pk_mul_f32 v[0:1], v[0:1], v[4:5] op_sel_hi:[1,0]
	v_pk_mul_f32 v[2:3], v[2:3], v[4:5] op_sel_hi:[1,0]
	v_cvt_pk_bf16_f32 v0, v0, v1
	v_cvt_pk_bf16_f32 v1, v2, v3
	global_store_dwordx2 v[8:9], v[0:1], off
	s_cbranch_scc0 .LBB0_999

; #define LAS __attribute__((address_space(3)))
; __device__ __forceinline__ unsigned cvt_pk_bf16(float lo, float hi) { f32x2 f = {lo, hi}; bf16x2_t v = __builtin_convertvector(f, bf16x2_t); return __builtin_bit_cast(unsigned, v); }
; template <int MODE>
; __device__ __forceinline__ void sgemm_sample(LAS unsigned char* lds, const bf16_t* A, const bf16_t* Bt, int K, const float* resid, float* out, bf16_t* xb, float* ssq_out, const float* ssq_in) {
;     ...
;     for (int uu = u; uu < 2048; uu += gridDim.x * 8) {
;         const int rt = uu >> 6, ct = uu & 63; const int row = NTOKP + rt * 16 + fr, col0 = ct * 16 + fq * 4;
;         const bf16_t* ap = A + (size_t)row * K + fq * 8; const bf16_t* bp = Bt + (size_t)(ct * 16 + fr) * K + fq * 8;
;         f32x4 acc = {0.f, 0.f, 0.f, 0.f};
; #pragma unroll 8
;         for (int ks = 0; ks < K / 32; ++ks) {
;             const bf16x8 a = *(const bf16x8*)(ap + ks * 32); const bf16x8 b = *(const bf16x8*)(bp + ks * 32);
;             acc = __builtin_amdgcn_mfma_f32_16x16x32_bf16(b, a, acc, 0, 0, 0);
;         }
;         if (MODE == 0) {
;             const f32x4 x = *(const f32x4*)(resid + (size_t)(row - NTOKP) * D + col0) + acc;
;             *(f32x4*)(out + (size_t)row * D + col0) = x;
;             if (xb) { u32x2 wv; wv.x = cvt_pk_bf16(x[0], x[1]); wv.y = cvt_pk_bf16(x[2], x[3]); *(u32x2*)(xb + (size_t)row * D + col0) = wv; }
;             if (ssq_out) {
;                 float ss = (x[0] * x[0] + x[1] * x[1]) + (x[2] * x[2] + x[3] * x[3]); ss += __shfl_xor(ss, 16); ss += __shfl_xor(ss, 32);
;                 if (fq == 0) *(LAS float*)(lds + (w * 16 + fr) * 4) = ss;
;                 __syncthreads();
;                 if (tid < 16) { float t = 0.f;
; #pragma unroll
;                     for (int i = 0; i < 8; ++i) t += *(const LAS float*)(lds + (i * 16 + tid) * 4);
;                     const int g = (uu & 63) >> 3; float* sp = ssq_out + (size_t)(NTOKP + rt * 16 + tid) * 16; sp[g] = t; sp[8 + g] = 0.f; }
;                 __syncthreads();
;             }
.LBB0_1168:
	s_and_b32 s6, s15, 63
	v_lshl_or_b32 v4, s6, 15, v21
	s_ashr_i32 s6, s3, 2
	s_and_b32 s6, s6, -16
	s_add_i32 s6, s6, 0x8000
	v_or_b32_e32 v12, s6, v17
	v_ashrrev_i32_e32 v13, 31, v12
	v_lshlrev_b64 v[8:9], 11, v[12:13]
	v_lshl_add_u64 v[10:11], v[6:7], 0, v[4:5]
	v_lshl_add_u64 v[14:15], v[6:7], 0, v[8:9]
	s_mov_b64 s[18:19], 0
	v_mov_b32_e32 v0, 0
	v_mov_b32_e32 v1, v5
	v_mov_b32_e32 v2, v5
	v_mov_b32_e32 v3, v5
	s_bfe_u32 s96, s2, 0x20003
	s_lshl_b32 s96, s96, 9
	s_mov_b32 s97, 0
.LBB0_1169:
	v_lshl_add_u64 v[24:25], v[14:15], 0, s[96:97]
	v_add_co_u32_e32 v60, vcc, 0x15780000, v24
	v_lshl_add_u64 v[26:27], v[10:11], 0, s[96:97]
	s_add_i32 s96, s96, 0x200
	s_cmpk_eq_i32 s96, 0x800
	s_cselect_b32 s96, 0, s96
	s_nop 0
	v_addc_co_u32_e32 v61, vcc, 0, v25, vcc
	v_add_co_u32_e32 v62, vcc, 0x1040000, v26
	s_add_u32 s18, s18, 0x200
	s_nop 0
	v_addc_co_u32_e32 v63, vcc, 0, v27, vcc
	global_load_dwordx4 v[24:27], v[60:61], off
	global_load_dwordx4 v[28:31], v[60:61], off offset:64
	global_load_dwordx4 v[32:35], v[60:61], off offset:128
	global_load_dwordx4 v[36:39], v[60:61], off offset:192
	global_load_dwordx4 v[40:43], v[60:61], off offset:256
	global_load_dwordx4 v[44:47], v[62:63], off
	global_load_dwordx4 v[48:51], v[62:63], off offset:64
	global_load_dwordx4 v[52:55], v[62:63], off offset:128
	global_load_dwordx4 v[56:59], v[62:63], off offset:192
	s_addc_u32 s19, s19, 0
	s_cmpk_eq_i32 s18, 0x800
	s_waitcnt vmcnt(3)
	v_mfma_f32_16x16x32_bf16 v[0:3], v[44:47], v[24:27], v[0:3]
	global_load_dwordx4 v[24:27], v[62:63], off offset:256
	s_waitcnt vmcnt(3)
	v_mfma_f32_16x16x32_bf16 v[0:3], v[48:51], v[28:31], v[0:3]
	global_load_dwordx4 v[28:31], v[62:63], off offset:320
	s_waitcnt vmcnt(3)
	v_mfma_f32_16x16x32_bf16 v[0:3], v[52:55], v[32:35], v[0:3]
	global_load_dwordx4 v[32:35], v[60:61], off offset:320
	s_waitcnt vmcnt(3)
	v_mfma_f32_16x16x32_bf16 v[0:3], v[56:59], v[36:39], v[0:3]
	global_load_dwordx4 v[36:39], v[62:63], off offset:384
	global_load_dwordx4 v[44:47], v[60:61], off offset:384
	s_waitcnt vmcnt(4)
	v_mfma_f32_16x16x32_bf16 v[0:3], v[24:27], v[40:43], v[0:3]
	global_load_dwordx4 v[24:27], v[62:63], off offset:448
	s_waitcnt vmcnt(3)
	v_mfma_f32_16x16x32_bf16 v[0:3], v[28:31], v[32:35], v[0:3]
	global_load_dwordx4 v[28:31], v[60:61], off offset:448
	s_waitcnt vmcnt(2)
	v_mfma_f32_16x16x32_bf16 v[0:3], v[36:39], v[44:47], v[0:3]
	s_waitcnt vmcnt(0)
	v_mfma_f32_16x16x32_bf16 v[0:3], v[24:27], v[28:31], v[0:3]
	s_cbranch_scc0 .LBB0_1169
	s_and_b32 s20, s3, 63
	v_lshl_or_b32 v24, s20, 4, v18
	v_lshlrev_b64 v[14:15], 12, v[12:13]
	v_lshl_add_u64 v[10:11], s[10:11], 0, v[14:15]
	v_lshlrev_b32_e32 v4, 2, v24
	v_lshl_add_u64 v[10:11], v[10:11], 0, v[4:5]
	v_add_co_u32_e32 v10, vcc, 0xf8000000, v10
	v_lshl_add_u64 v[14:15], s[90:91], 0, v[14:15]
	s_nop 0
	v_addc_co_u32_e32 v11, vcc, -1, v11, vcc
	global_load_dwordx4 v[10:13], v[10:11], off
	s_waitcnt vmcnt(0)
	v_pk_add_f32 v[2:3], v[2:3], v[12:13]
	v_pk_add_f32 v[0:1], v[0:1], v[10:11]
	v_mul_f32_e32 v11, v3, v3
	v_mul_f32_e32 v10, v1, v1
	v_fmac_f32_e32 v10, v0, v0
	v_fmac_f32_e32 v11, v2, v2
	v_add_f32_e32 v12, v10, v11
	ds_bpermute_b32 v13, v19, v12
	v_lshl_add_u64 v[10:11], v[14:15], 0, v[4:5]
	global_store_dwordx4 v[10:11], v[0:3], off
	v_cvt_pk_bf16_f32 v10, v0, v1
	v_cvt_pk_bf16_f32 v11, v2, v3
	s_waitcnt lgkmcnt(0)
	v_add_f32_e32 v0, v12, v13
	ds_bpermute_b32 v1, v20, v0
	v_lshl_add_u64 v[2:3], s[12:13], 0, v[8:9]
	v_lshlrev_b32_e32 v4, 1, v24
	v_lshl_add_u64 v[2:3], v[2:3], 0, v[4:5]
	global_store_dwordx2 v[2:3], v[10:11], off
	s_and_saveexec_b64 s[18:19], s[0:1]
	s_cbranch_execz .LBB0_1172
	s_waitcnt lgkmcnt(0)
	v_add_f32_e32 v0, v0, v1
	ds_write_b32 v22, v0

; template <int MODE>
; __device__ __forceinline__ void sgemm_sample(LAS unsigned char* lds, const bf16_t* A, const bf16_t* Bt, int K, const float* resid, float* out, bf16_t* xb, float* ssq_out, const float* ssq_in) {
;     ...
;     for (int uu = u; uu < 2048; uu += gridDim.x * 8) {
;         const int rt = uu >> 6, ct = uu & 63; const int row = NTOKP + rt * 16 + fr, col0 = ct * 16 + fq * 4;
;         const bf16_t* ap = A + (size_t)row * K + fq * 8; const bf16_t* bp = Bt + (size_t)(ct * 16 + fr) * K + fq * 8;
;         f32x4 acc = {0.f, 0.f, 0.f, 0.f};
; #pragma unroll 8
;         for (int ks = 0; ks < K / 32; ++ks) {
;             const bf16x8 a = *(const bf16x8*)(ap + ks * 32); const bf16x8 b = *(const bf16x8*)(bp + ks * 32);
;             acc = __builtin_amdgcn_mfma_f32_16x16x32_bf16(b, a, acc, 0, 0, 0);
;         }
;         if (MODE == 0) {
;             const f32x4 x = *(const f32x4*)(resid + (size_t)(row - NTOKP) * D + col0) + acc;
;             *(f32x4*)(out + (size_t)row * D + col0) = x;
.LBB0_1348:
	s_ashr_i32 s0, s3, 2
	s_and_b32 s0, s0, -16
	v_add_u32_e32 v8, s0, v16
	s_lshl_b32 s0, s3, 4
	s_and_b32 s10, s0, 0x3f0
	v_or_b32_e32 v0, s10, v14
	v_mul_u32_u24_e32 v0, 0xb00, v0
	v_mad_i64_i32 v[10:11], s[0:1], v8, s5, v[6:7]
	v_lshlrev_b32_e32 v4, 1, v0
	v_ashrrev_i32_e32 v9, 31, v8
	v_lshl_add_u64 v[12:13], v[6:7], 0, v[4:5]
	s_mov_b64 s[0:1], 0
	v_mov_b32_e32 v0, 0
	s_waitcnt lgkmcnt(0)
	v_mov_b32_e32 v1, v5
	v_mov_b32_e32 v2, v5
	v_mov_b32_e32 v3, v5
	s_bfe_u32 s96, s2, 0x30003
	s_lshl_b32 s96, s96, 9
	s_mov_b32 s97, 0
.LBB0_1349:
	v_lshl_add_u64 v[18:19], v[10:11], 0, s[96:97]
	v_add_co_u32_e32 v54, vcc, 0x22c0000, v18
	v_lshl_add_u64 v[20:21], v[12:13], 0, s[96:97]
	s_add_i32 s96, s96, 0x200
	s_cmpk_eq_i32 s96, 0x1600
	s_cselect_b32 s96, 0, s96
	s_nop 0
	v_addc_co_u32_e32 v55, vcc, 0, v19, vcc
	v_add_co_u32_e32 v56, vcc, 0x1d40000, v20
	s_add_u32 s0, s0, 0x200
	s_nop 0
	v_addc_co_u32_e32 v57, vcc, 0, v21, vcc
	global_load_dwordx4 v[18:21], v[54:55], off
	global_load_dwordx4 v[22:25], v[54:55], off offset:64
	global_load_dwordx4 v[26:29], v[54:55], off offset:128
	global_load_dwordx4 v[30:33], v[54:55], off offset:192
	global_load_dwordx4 v[34:37], v[54:55], off offset:256
	global_load_dwordx4 v[38:41], v[56:57], off
	global_load_dwordx4 v[42:45], v[56:57], off offset:64
	global_load_dwordx4 v[46:49], v[56:57], off offset:128
	global_load_dwordx4 v[50:53], v[56:57], off offset:192
	s_addc_u32 s1, s1, 0
	s_cmpk_eq_i32 s0, 0x1600
	s_waitcnt vmcnt(3)
	v_mfma_f32_16x16x32_bf16 v[0:3], v[38:41], v[18:21], v[0:3]
	global_load_dwordx4 v[18:21], v[56:57], off offset:256
	s_waitcnt vmcnt(3)
	v_mfma_f32_16x16x32_bf16 v[0:3], v[42:45], v[22:25], v[0:3]
	global_load_dwordx4 v[22:25], v[56:57], off offset:320
	s_waitcnt vmcnt(3)
	v_mfma_f32_16x16x32_bf16 v[0:3], v[46:49], v[26:29], v[0:3]
	global_load_dwordx4 v[26:29], v[54:55], off offset:320
	s_waitcnt vmcnt(3)
	v_mfma_f32_16x16x32_bf16 v[0:3], v[50:53], v[30:33], v[0:3]
	global_load_dwordx4 v[30:33], v[56:57], off offset:384
	global_load_dwordx4 v[38:41], v[54:55], off offset:384
	s_waitcnt vmcnt(4)
	v_mfma_f32_16x16x32_bf16 v[0:3], v[18:21], v[34:37], v[0:3]
	global_load_dwordx4 v[18:21], v[56:57], off offset:448
	s_waitcnt vmcnt(3)
	v_mfma_f32_16x16x32_bf16 v[0:3], v[22:25], v[26:29], v[0:3]
	global_load_dwordx4 v[22:25], v[54:55], off offset:448
	s_waitcnt vmcnt(2)
	v_mfma_f32_16x16x32_bf16 v[0:3], v[30:33], v[38:41], v[0:3]
	s_waitcnt vmcnt(0)
	v_mfma_f32_16x16x32_bf16 v[0:3], v[18:21], v[22:25], v[0:3]
	s_cbranch_scc0 .LBB0_1349
	v_or_b32_e32 v4, s10, v15
	v_lshlrev_b64 v[12:13], 12, v[8:9]
	v_lshl_add_u64 v[8:9], s[8:9], 0, v[12:13]
	v_lshlrev_b32_e32 v4, 2, v4
	v_lshl_add_u64 v[8:9], v[8:9], 0, v[4:5]
	v_add_co_u32_e32 v8, vcc, 0xf8000000, v8
	s_add_i32 s3, s3, s4
	s_nop 0
	v_addc_co_u32_e32 v9, vcc, -1, v9, vcc
	global_load_dwordx4 v[8:11], v[8:9], off
	v_lshl_add_u64 v[12:13], s[90:91], 0, v[12:13]
	v_lshl_add_u64 v[12:13], v[12:13], 0, v[4:5]
	s_cmpk_gt_i32 s3, 0x7ff
	s_waitcnt vmcnt(0)
	v_pk_add_f32 v[2:3], v[2:3], v[10:11]
	v_pk_add_f32 v[0:1], v[0:1], v[8:9]
	global_store_dwordx4 v[12:13], v[0:3], off
	s_cbranch_scc0 .LBB0_1348
